# P4 publishes everything with write-through stores (scan outputs, final states, fp8 weight copies) so barrier 5 has no dirty L2 data to write back
# baseline (speedup 1.0000x reference)
.LBB0_608:
	s_mov_b64 s[78:79], -1
	s_and_b64 vcc, exec, s[54:55]
	s_cbranch_vccz .LBB0_610
	s_ashr_i32 s77, s76, 31
	s_lshl_b64 s[14:15], s[76:77], 15
	v_lshl_add_u64 v[2:3], v[124:125], 0, s[14:15]
	s_waitcnt vmcnt(13)
	v_add_co_u32_e32 v8, vcc, 0x2000, v2
	global_store_dwordx4 v[2:3], v[52:55], off sc1
	s_nop 0
	v_addc_co_u32_e32 v9, vcc, 0, v3, vcc
	global_store_dwordx4 v[8:9], v[48:51], off sc1
	v_add_co_u32_e32 v8, vcc, 0x4000, v2
	s_mov_b64 s[78:79], 0
	s_nop 0
	v_addc_co_u32_e32 v9, vcc, 0, v3, vcc
	v_add_co_u32_e32 v2, vcc, 0x6000, v2
	global_store_dwordx4 v[8:9], v[56:59], off sc1
	s_nop 0
	v_addc_co_u32_e32 v3, vcc, 0, v3, vcc
	global_store_dwordx4 v[2:3], v[60:63], off sc1

.LBB0_633:
	s_mov_b64 s[76:77], -1
	s_and_b64 vcc, exec, s[54:55]
	s_mov_b64 s[78:79], -1
	s_cbranch_vccz .LBB0_575
	s_mov_b64 s[22:23], s[62:63]
	v_readlane_b32 s56, v254, 0
	v_readlane_b32 s57, v254, 1
	v_readlane_b32 s58, v254, 2
	v_readlane_b32 s59, v254, 3
	v_readlane_b32 s60, v254, 4
	v_readlane_b32 s61, v254, 5
	s_ashr_i32 s15, s14, 31
	v_readlane_b32 s62, v254, 6
	v_readlane_b32 s63, v254, 7
	s_mov_b64 s[56:57], s[60:61]
	s_lshl_b64 s[12:13], s[14:15], 17
	s_mov_b64 s[58:59], s[62:63]
	s_add_u32 s12, s58, s12
	s_addc_u32 s13, s59, s13
	v_lshlrev_b32_e32 v0, 2, v110
	v_lshl_add_u64 v[2:3], s[12:13], 0, v[0:1]
	s_lshl_b32 s20, s20, 2
	v_lshl_add_u64 v[2:3], v[2:3], 0, s[20:21]
	v_lshl_add_u64 v[2:3], v[114:115], 2, v[2:3]
	s_mov_b64 s[12:13], 0x4000000
	s_waitcnt vmcnt(13)
	v_lshl_add_u64 v[8:9], v[2:3], 0, s[12:13]
	s_brev_b32 s12, 32
	v_add_co_u32_e32 v2, vcc, s12, v2
	s_cmp_lg_u32 s67, 0
	s_nop 0
	v_addc_co_u32_e32 v3, vcc, 0, v3, vcc
	global_store_dword v[2:3], v64, off sc1
	global_store_dword v[8:9], v65, off offset:1024 sc1
	global_store_dword v[8:9], v66, off offset:2048 sc1
	global_store_dword v[8:9], v67, off offset:3072 sc1
	global_store_dword v[8:9], v60, off offset:64 sc1
	global_store_dword v[8:9], v61, off offset:1088 sc1
	global_store_dword v[8:9], v62, off offset:2112 sc1
	global_store_dword v[8:9], v63, off offset:3136 sc1
	global_store_dword v[8:9], v56, off offset:128 sc1
	global_store_dword v[8:9], v57, off offset:1152 sc1
	global_store_dword v[8:9], v58, off offset:2176 sc1
	global_store_dword v[8:9], v59, off offset:3200 sc1
	global_store_dword v[8:9], v52, off offset:192 sc1
	global_store_dword v[8:9], v53, off offset:1216 sc1
	global_store_dword v[8:9], v54, off offset:2240 sc1
	global_store_dword v[8:9], v55, off offset:3264 sc1
	s_cbranch_scc1 .LBB0_574
	s_mov_b64 s[12:13], exec
	v_readlane_b32 s16, v254, 55
	v_readlane_b32 s17, v254, 56
	s_and_b64 s[16:17], s[12:13], s[16:17]
	s_mov_b64 exec, s[16:17]
	s_cbranch_execz .LBB0_637
	v_readlane_b32 s56, v254, 0
	s_lshl_b32 s16, s14, 7
	v_readlane_b32 s57, v254, 1
	v_readlane_b32 s58, v254, 2
	v_readlane_b32 s59, v254, 3
	v_readlane_b32 s60, v254, 4
	v_readlane_b32 s61, v254, 5
	s_ashr_i32 s17, s16, 31
	v_readlane_b32 s62, v254, 6
	v_readlane_b32 s63, v254, 7
	s_mov_b64 s[56:57], s[60:61]
	s_lshl_b64 s[16:17], s[16:17], 2
	s_mov_b64 s[58:59], s[62:63]
	s_add_u32 s16, s58, s16
	s_addc_u32 s17, s59, s17
	v_readlane_b32 s26, v254, 61
	v_readlane_b32 s27, v254, 62
	s_add_u32 s16, s16, s26
	s_addc_u32 s17, s17, s27
	s_waitcnt vmcnt(24)
	v_mov_b32_e32 v127, v1
	v_lshl_add_u64 v[2:3], s[16:17], 0, v[126:127]
	v_add_co_u32_e32 v2, vcc, 0x5000000, v2
	s_nop 1
	v_addc_co_u32_e32 v3, vcc, 0, v3, vcc
	global_store_dwordx4 v[2:3], v[48:51], off sc1
.LBB0_637:
	s_or_b64 exec, exec, s[12:13]
	s_and_saveexec_b64 s[12:13], s[4:5]
	s_cbranch_execz .LBB0_573
	v_readlane_b32 s56, v254, 0
	v_readlane_b32 s57, v254, 1
	v_readlane_b32 s58, v254, 2
	v_readlane_b32 s59, v254, 3
	v_readlane_b32 s60, v254, 4
	v_readlane_b32 s61, v254, 5
	v_readlane_b32 s62, v254, 6
	v_readlane_b32 s63, v254, 7
	s_mov_b64 s[56:57], s[60:61]
	s_lshl_b64 s[14:15], s[14:15], 2
	s_mov_b64 s[58:59], s[62:63]
	s_add_u32 s14, s58, s14
	s_addc_u32 s15, s59, s15
	global_store_dword v171, v129, s[14:15] sc1
	s_branch .LBB0_573

.Lcp_md_2:
	s_add_u32 s45, s43, 7
	s_lshl_b32 s53, s5, s45
	s_lshl_b32 s4, s1, 7
	s_add_u32 s53, s53, s4
	s_add_u32 s80, s6, s53
	s_addc_u32 s81, s7, 0
	s_add_u32 s45, s43, 5
	s_lshl_b32 s4, 1, s45
	s_add_u32 s82, s80, s4
	s_addc_u32 s83, s81, 0
	s_add_u32 s84, s82, s4
	s_addc_u32 s85, s83, 0
	s_add_u32 s86, s84, s4
	s_addc_u32 s87, s85, 0
	s_add_u32 s45, s59, 5
	s_lshl_b32 s4, s1, s45
	s_lshl_b32 s5, s5, 7
	s_add_u32 s4, s4, s5
	s_add_u32 s92, s8, s4
	s_addc_u32 s93, s9, 0
	s_add_u32 s45, s43, 2
	v_lshlrev_b32_e32 v194, s45, v200
	v_add_u32_e32 v194, v194, v201
	s_lshl_b32 s4, 1, s43
	v_add_u32_e32 v195, s4, v194
	v_add_u32_e32 v196, s4, v195
	v_add_u32_e32 v197, s4, v196
	global_load_dwordx4 v[128:131], v194, s[80:81]
	global_load_dwordx4 v[132:135], v195, s[80:81]
	global_load_dwordx4 v[136:139], v196, s[80:81]
	global_load_dwordx4 v[140:143], v197, s[80:81]
	global_load_dwordx4 v[144:147], v194, s[82:83]
	global_load_dwordx4 v[148:151], v195, s[82:83]
	global_load_dwordx4 v[152:155], v196, s[82:83]
	global_load_dwordx4 v[156:159], v197, s[82:83]
	global_load_dwordx4 v[160:163], v194, s[84:85]
	global_load_dwordx4 v[164:167], v195, s[84:85]
	global_load_dwordx4 v[168:171], v196, s[84:85]
	global_load_dwordx4 v[172:175], v197, s[84:85]
	global_load_dwordx4 v[176:179], v194, s[86:87]
	global_load_dwordx4 v[180:183], v195, s[86:87]
	global_load_dwordx4 v[186:189], v196, s[86:87]
	global_load_dwordx4 v[190:193], v197, s[86:87]
	s_waitcnt vmcnt(32)
	v_pk_mul_f32 v[0:1], v[0:1], s[40:41]
	v_pk_mul_f32 v[2:3], v[2:3], s[40:41]
	v_pk_mul_f32 v[4:5], v[4:5], s[40:41]
	v_pk_mul_f32 v[6:7], v[6:7], s[40:41]
	v_pk_mul_f32 v[8:9], v[8:9], s[40:41]
	v_pk_mul_f32 v[10:11], v[10:11], s[40:41]
	v_pk_mul_f32 v[12:13], v[12:13], s[40:41]
	v_pk_mul_f32 v[14:15], v[14:15], s[40:41]
	v_pk_mul_f32 v[16:17], v[16:17], s[40:41]
	v_pk_mul_f32 v[18:19], v[18:19], s[40:41]
	v_pk_mul_f32 v[20:21], v[20:21], s[40:41]
	v_pk_mul_f32 v[22:23], v[22:23], s[40:41]
	v_pk_mul_f32 v[24:25], v[24:25], s[40:41]
	v_pk_mul_f32 v[26:27], v[26:27], s[40:41]
	v_pk_mul_f32 v[28:29], v[28:29], s[40:41]
	v_pk_mul_f32 v[30:31], v[30:31], s[40:41]
	v_pk_mul_f32 v[32:33], v[32:33], s[40:41]
	v_pk_mul_f32 v[34:35], v[34:35], s[40:41]
	v_pk_mul_f32 v[36:37], v[36:37], s[40:41]
	v_pk_mul_f32 v[38:39], v[38:39], s[40:41]
	v_pk_mul_f32 v[40:41], v[40:41], s[40:41]
	v_pk_mul_f32 v[42:43], v[42:43], s[40:41]
	v_pk_mul_f32 v[44:45], v[44:45], s[40:41]
	v_pk_mul_f32 v[46:47], v[46:47], s[40:41]
	v_pk_mul_f32 v[48:49], v[48:49], s[40:41]
	v_pk_mul_f32 v[50:51], v[50:51], s[40:41]
	v_pk_mul_f32 v[52:53], v[52:53], s[40:41]
	v_pk_mul_f32 v[54:55], v[54:55], s[40:41]
	v_pk_mul_f32 v[56:57], v[56:57], s[40:41]
	v_pk_mul_f32 v[58:59], v[58:59], s[40:41]
	v_pk_mul_f32 v[60:61], v[60:61], s[40:41]
	v_pk_mul_f32 v[62:63], v[62:63], s[40:41]
	v_cvt_pk_fp8_f32 v0, v0, v4
	v_cvt_pk_fp8_f32 v1, v1, v5
	v_cvt_pk_fp8_f32 v2, v2, v6
	v_cvt_pk_fp8_f32 v3, v3, v7
	v_cvt_pk_fp8_f32 v0, v8, v12 op_sel:[0,0,1]
	v_cvt_pk_fp8_f32 v1, v9, v13 op_sel:[0,0,1]
	v_cvt_pk_fp8_f32 v2, v10, v14 op_sel:[0,0,1]
	v_cvt_pk_fp8_f32 v3, v11, v15 op_sel:[0,0,1]
	v_cvt_pk_fp8_f32 v16, v16, v20
	v_cvt_pk_fp8_f32 v17, v17, v21
	v_cvt_pk_fp8_f32 v18, v18, v22
	v_cvt_pk_fp8_f32 v19, v19, v23
	v_cvt_pk_fp8_f32 v16, v24, v28 op_sel:[0,0,1]
	v_cvt_pk_fp8_f32 v17, v25, v29 op_sel:[0,0,1]
	v_cvt_pk_fp8_f32 v18, v26, v30 op_sel:[0,0,1]
	v_cvt_pk_fp8_f32 v19, v27, v31 op_sel:[0,0,1]
	v_cvt_pk_fp8_f32 v32, v32, v36
	v_cvt_pk_fp8_f32 v33, v33, v37
	v_cvt_pk_fp8_f32 v34, v34, v38
	v_cvt_pk_fp8_f32 v35, v35, v39
	v_cvt_pk_fp8_f32 v32, v40, v44 op_sel:[0,0,1]
	v_cvt_pk_fp8_f32 v33, v41, v45 op_sel:[0,0,1]
	v_cvt_pk_fp8_f32 v34, v42, v46 op_sel:[0,0,1]
	v_cvt_pk_fp8_f32 v35, v43, v47 op_sel:[0,0,1]
	v_cvt_pk_fp8_f32 v48, v48, v52
	v_cvt_pk_fp8_f32 v49, v49, v53
	v_cvt_pk_fp8_f32 v50, v50, v54
	v_cvt_pk_fp8_f32 v51, v51, v55
	v_cvt_pk_fp8_f32 v48, v56, v60 op_sel:[0,0,1]
	v_cvt_pk_fp8_f32 v49, v57, v61 op_sel:[0,0,1]
	v_cvt_pk_fp8_f32 v50, v58, v62 op_sel:[0,0,1]
	v_cvt_pk_fp8_f32 v51, v59, v63 op_sel:[0,0,1]
	s_nop 0
	ds_write2_b32 v198, v0, v16 offset0:0 offset1:8
	ds_write2_b32 v198, v32, v48 offset0:16 offset1:24
	ds_write2_b32 v198, v1, v17 offset0:36 offset1:44
	ds_write2_b32 v198, v33, v49 offset0:52 offset1:60
	ds_write2_b32 v198, v2, v18 offset0:72 offset1:80
	ds_write2_b32 v198, v34, v50 offset0:88 offset1:96
	ds_write2_b32 v198, v3, v19 offset0:108 offset1:116
	ds_write2_b32 v198, v35, v51 offset0:124 offset1:132
	v_lshlrev_b32_e32 v8, s55, v200
	v_add_u32_e32 v8, v8, v201
	s_add_u32 s45, s55, 3
	s_lshl_b32 s4, 1, s45
	v_add_u32_e32 v24, s4, v8
	v_add_u32_e32 v40, s4, v24
	v_add_u32_e32 v56, s4, v40
	s_waitcnt lgkmcnt(0)
	ds_read_b128 v[4:7], v199 offset:0
	ds_read_b128 v[20:23], v199 offset:1152
	ds_read_b128 v[36:39], v199 offset:2304
	ds_read_b128 v[52:55], v199 offset:3456
	s_waitcnt lgkmcnt(3)
	global_store_dwordx4 v8, v[4:7], s[88:89] sc1
	s_waitcnt lgkmcnt(2)
	global_store_dwordx4 v24, v[20:23], s[88:89] sc1
	s_waitcnt lgkmcnt(1)
	global_store_dwordx4 v40, v[36:39], s[88:89] sc1
	s_waitcnt lgkmcnt(0)
	global_store_dwordx4 v56, v[52:55], s[88:89] sc1
	s_min_u32 s5, s3, 9215
	s_add_u32 s3, s3, 384
	s_cmp_lt_u32 s5, 0x400
	s_cbranch_scc1 .Lcp_m0_3
	s_cmp_lt_u32 s5, 0x1400
	s_cbranch_scc1 .Lcp_m1_3
	s_sub_u32 s5, s5, 0x1400
	s_and_b32 s1, s5, 63
	s_lshr_b32 s5, s5, 6
	s_mov_b32 s43, 13
	s_mov_b32 s55, 13
	s_mov_b64 s[6:7], s[94:95]
	s_add_u32 s8, s28, 0x4500000
	s_addc_u32 s9, s29, 0
	s_branch .Lcp_md_3

.Lcp_md_3:
	s_add_u32 s45, s43, 7
	s_lshl_b32 s53, s5, s45
	s_lshl_b32 s4, s1, 7
	s_add_u32 s53, s53, s4
	s_add_u32 s80, s6, s53
	s_addc_u32 s81, s7, 0
	s_add_u32 s45, s43, 5
	s_lshl_b32 s4, 1, s45
	s_add_u32 s82, s80, s4
	s_addc_u32 s83, s81, 0
	s_add_u32 s84, s82, s4
	s_addc_u32 s85, s83, 0
	s_add_u32 s86, s84, s4
	s_addc_u32 s87, s85, 0
	s_add_u32 s45, s55, 5
	s_lshl_b32 s4, s1, s45
	s_lshl_b32 s5, s5, 7
	s_add_u32 s4, s4, s5
	s_add_u32 s88, s8, s4
	s_addc_u32 s89, s9, 0
	s_add_u32 s45, s43, 2
	v_lshlrev_b32_e32 v194, s45, v200
	v_add_u32_e32 v194, v194, v201
	s_lshl_b32 s4, 1, s43
	v_add_u32_e32 v195, s4, v194
	v_add_u32_e32 v196, s4, v195
	v_add_u32_e32 v197, s4, v196
	global_load_dwordx4 v[0:3], v194, s[80:81]
	global_load_dwordx4 v[4:7], v195, s[80:81]
	global_load_dwordx4 v[8:11], v196, s[80:81]
	global_load_dwordx4 v[12:15], v197, s[80:81]
	global_load_dwordx4 v[16:19], v194, s[82:83]
	global_load_dwordx4 v[20:23], v195, s[82:83]
	global_load_dwordx4 v[24:27], v196, s[82:83]
	global_load_dwordx4 v[28:31], v197, s[82:83]
	global_load_dwordx4 v[32:35], v194, s[84:85]
	global_load_dwordx4 v[36:39], v195, s[84:85]
	global_load_dwordx4 v[40:43], v196, s[84:85]
	global_load_dwordx4 v[44:47], v197, s[84:85]
	global_load_dwordx4 v[48:51], v194, s[86:87]
	global_load_dwordx4 v[52:55], v195, s[86:87]
	global_load_dwordx4 v[56:59], v196, s[86:87]
	global_load_dwordx4 v[60:63], v197, s[86:87]
	s_waitcnt vmcnt(36)
	v_pk_mul_f32 v[64:65], v[64:65], s[40:41]
	v_pk_mul_f32 v[66:67], v[66:67], s[40:41]
	v_pk_mul_f32 v[68:69], v[68:69], s[40:41]
	v_pk_mul_f32 v[70:71], v[70:71], s[40:41]
	v_pk_mul_f32 v[72:73], v[72:73], s[40:41]
	v_pk_mul_f32 v[74:75], v[74:75], s[40:41]
	v_pk_mul_f32 v[76:77], v[76:77], s[40:41]
	v_pk_mul_f32 v[78:79], v[78:79], s[40:41]
	v_pk_mul_f32 v[80:81], v[80:81], s[40:41]
	v_pk_mul_f32 v[82:83], v[82:83], s[40:41]
	v_pk_mul_f32 v[84:85], v[84:85], s[40:41]
	v_pk_mul_f32 v[86:87], v[86:87], s[40:41]
	v_pk_mul_f32 v[88:89], v[88:89], s[40:41]
	v_pk_mul_f32 v[90:91], v[90:91], s[40:41]
	v_pk_mul_f32 v[92:93], v[92:93], s[40:41]
	v_pk_mul_f32 v[94:95], v[94:95], s[40:41]
	v_pk_mul_f32 v[96:97], v[96:97], s[40:41]
	v_pk_mul_f32 v[98:99], v[98:99], s[40:41]
	v_pk_mul_f32 v[100:101], v[100:101], s[40:41]
	v_pk_mul_f32 v[102:103], v[102:103], s[40:41]
	v_pk_mul_f32 v[104:105], v[104:105], s[40:41]
	v_pk_mul_f32 v[106:107], v[106:107], s[40:41]
	v_pk_mul_f32 v[108:109], v[108:109], s[40:41]
	v_pk_mul_f32 v[110:111], v[110:111], s[40:41]
	v_pk_mul_f32 v[112:113], v[112:113], s[40:41]
	v_pk_mul_f32 v[114:115], v[114:115], s[40:41]
	v_pk_mul_f32 v[116:117], v[116:117], s[40:41]
	v_pk_mul_f32 v[118:119], v[118:119], s[40:41]
	v_pk_mul_f32 v[120:121], v[120:121], s[40:41]
	v_pk_mul_f32 v[122:123], v[122:123], s[40:41]
	v_pk_mul_f32 v[124:125], v[124:125], s[40:41]
	v_pk_mul_f32 v[126:127], v[126:127], s[40:41]
	v_cvt_pk_fp8_f32 v64, v64, v68
	v_cvt_pk_fp8_f32 v65, v65, v69
	v_cvt_pk_fp8_f32 v66, v66, v70
	v_cvt_pk_fp8_f32 v67, v67, v71
	v_cvt_pk_fp8_f32 v64, v72, v76 op_sel:[0,0,1]
	v_cvt_pk_fp8_f32 v65, v73, v77 op_sel:[0,0,1]
	v_cvt_pk_fp8_f32 v66, v74, v78 op_sel:[0,0,1]
	v_cvt_pk_fp8_f32 v67, v75, v79 op_sel:[0,0,1]
	v_cvt_pk_fp8_f32 v80, v80, v84
	v_cvt_pk_fp8_f32 v81, v81, v85
	v_cvt_pk_fp8_f32 v82, v82, v86
	v_cvt_pk_fp8_f32 v83, v83, v87
	v_cvt_pk_fp8_f32 v80, v88, v92 op_sel:[0,0,1]
	v_cvt_pk_fp8_f32 v81, v89, v93 op_sel:[0,0,1]
	v_cvt_pk_fp8_f32 v82, v90, v94 op_sel:[0,0,1]
	v_cvt_pk_fp8_f32 v83, v91, v95 op_sel:[0,0,1]
	v_cvt_pk_fp8_f32 v96, v96, v100
	v_cvt_pk_fp8_f32 v97, v97, v101
	v_cvt_pk_fp8_f32 v98, v98, v102
	v_cvt_pk_fp8_f32 v99, v99, v103
	v_cvt_pk_fp8_f32 v96, v104, v108 op_sel:[0,0,1]
	v_cvt_pk_fp8_f32 v97, v105, v109 op_sel:[0,0,1]
	v_cvt_pk_fp8_f32 v98, v106, v110 op_sel:[0,0,1]
	v_cvt_pk_fp8_f32 v99, v107, v111 op_sel:[0,0,1]
	v_cvt_pk_fp8_f32 v112, v112, v116
	v_cvt_pk_fp8_f32 v113, v113, v117
	v_cvt_pk_fp8_f32 v114, v114, v118
	v_cvt_pk_fp8_f32 v115, v115, v119
	v_cvt_pk_fp8_f32 v112, v120, v124 op_sel:[0,0,1]
	v_cvt_pk_fp8_f32 v113, v121, v125 op_sel:[0,0,1]
	v_cvt_pk_fp8_f32 v114, v122, v126 op_sel:[0,0,1]
	v_cvt_pk_fp8_f32 v115, v123, v127 op_sel:[0,0,1]
	s_nop 0
	ds_write2_b32 v198, v64, v80 offset0:0 offset1:8
	ds_write2_b32 v198, v96, v112 offset0:16 offset1:24
	ds_write2_b32 v198, v65, v81 offset0:36 offset1:44
	ds_write2_b32 v198, v97, v113 offset0:52 offset1:60
	ds_write2_b32 v198, v66, v82 offset0:72 offset1:80
	ds_write2_b32 v198, v98, v114 offset0:88 offset1:96
	ds_write2_b32 v198, v67, v83 offset0:108 offset1:116
	ds_write2_b32 v198, v99, v115 offset0:124 offset1:132
	v_lshlrev_b32_e32 v72, s58, v200
	v_add_u32_e32 v72, v72, v201
	s_add_u32 s45, s58, 3
	s_lshl_b32 s4, 1, s45
	v_add_u32_e32 v88, s4, v72
	v_add_u32_e32 v104, s4, v88
	v_add_u32_e32 v120, s4, v104
	s_waitcnt lgkmcnt(0)
	ds_read_b128 v[68:71], v199 offset:0
	ds_read_b128 v[84:87], v199 offset:1152
	ds_read_b128 v[100:103], v199 offset:2304
	ds_read_b128 v[116:119], v199 offset:3456
	s_waitcnt lgkmcnt(3)
	global_store_dwordx4 v72, v[68:71], s[90:91] sc1
	s_waitcnt lgkmcnt(2)
	global_store_dwordx4 v88, v[84:87], s[90:91] sc1
	s_waitcnt lgkmcnt(1)
	global_store_dwordx4 v104, v[100:103], s[90:91] sc1
	s_waitcnt lgkmcnt(0)
	global_store_dwordx4 v120, v[116:119], s[90:91] sc1
	s_min_u32 s5, s3, 9215
	s_add_u32 s3, s3, 384
	s_cmp_lt_u32 s5, 0x400
	s_cbranch_scc1 .Lcp_m0_4
	s_cmp_lt_u32 s5, 0x1400
	s_cbranch_scc1 .Lcp_m1_4
	s_sub_u32 s5, s5, 0x1400
	s_and_b32 s1, s5, 63
	s_lshr_b32 s5, s5, 6
	s_mov_b32 s43, 13
	s_mov_b32 s58, 13
	s_mov_b64 s[6:7], s[94:95]
	s_add_u32 s8, s28, 0x4500000
	s_addc_u32 s9, s29, 0
	s_branch .Lcp_md_4

.Lcp_md_4:
	s_add_u32 s45, s43, 7
	s_lshl_b32 s53, s5, s45
	s_lshl_b32 s4, s1, 7
	s_add_u32 s53, s53, s4
	s_add_u32 s80, s6, s53
	s_addc_u32 s81, s7, 0
	s_add_u32 s45, s43, 5
	s_lshl_b32 s4, 1, s45
	s_add_u32 s82, s80, s4
	s_addc_u32 s83, s81, 0
	s_add_u32 s84, s82, s4
	s_addc_u32 s85, s83, 0
	s_add_u32 s86, s84, s4
	s_addc_u32 s87, s85, 0
	s_add_u32 s45, s58, 5
	s_lshl_b32 s4, s1, s45
	s_lshl_b32 s5, s5, 7
	s_add_u32 s4, s4, s5
	s_add_u32 s90, s8, s4
	s_addc_u32 s91, s9, 0
	s_add_u32 s45, s43, 2
	v_lshlrev_b32_e32 v194, s45, v200
	v_add_u32_e32 v194, v194, v201
	s_lshl_b32 s4, 1, s43
	v_add_u32_e32 v195, s4, v194
	v_add_u32_e32 v196, s4, v195
	v_add_u32_e32 v197, s4, v196
	global_load_dwordx4 v[64:67], v194, s[80:81]
	global_load_dwordx4 v[68:71], v195, s[80:81]
	global_load_dwordx4 v[72:75], v196, s[80:81]
	global_load_dwordx4 v[76:79], v197, s[80:81]
	global_load_dwordx4 v[80:83], v194, s[82:83]
	global_load_dwordx4 v[84:87], v195, s[82:83]
	global_load_dwordx4 v[88:91], v196, s[82:83]
	global_load_dwordx4 v[92:95], v197, s[82:83]
	global_load_dwordx4 v[96:99], v194, s[84:85]
	global_load_dwordx4 v[100:103], v195, s[84:85]
	global_load_dwordx4 v[104:107], v196, s[84:85]
	global_load_dwordx4 v[108:111], v197, s[84:85]
	global_load_dwordx4 v[112:115], v194, s[86:87]
	global_load_dwordx4 v[116:119], v195, s[86:87]
	global_load_dwordx4 v[120:123], v196, s[86:87]
	global_load_dwordx4 v[124:127], v197, s[86:87]
	s_waitcnt vmcnt(40)
	v_pk_mul_f32 v[128:129], v[128:129], s[40:41]
	v_pk_mul_f32 v[130:131], v[130:131], s[40:41]
	v_pk_mul_f32 v[132:133], v[132:133], s[40:41]
	v_pk_mul_f32 v[134:135], v[134:135], s[40:41]
	v_pk_mul_f32 v[136:137], v[136:137], s[40:41]
	v_pk_mul_f32 v[138:139], v[138:139], s[40:41]
	v_pk_mul_f32 v[140:141], v[140:141], s[40:41]
	v_pk_mul_f32 v[142:143], v[142:143], s[40:41]
	v_pk_mul_f32 v[144:145], v[144:145], s[40:41]
	v_pk_mul_f32 v[146:147], v[146:147], s[40:41]
	v_pk_mul_f32 v[148:149], v[148:149], s[40:41]
	v_pk_mul_f32 v[150:151], v[150:151], s[40:41]
	v_pk_mul_f32 v[152:153], v[152:153], s[40:41]
	v_pk_mul_f32 v[154:155], v[154:155], s[40:41]
	v_pk_mul_f32 v[156:157], v[156:157], s[40:41]
	v_pk_mul_f32 v[158:159], v[158:159], s[40:41]
	v_pk_mul_f32 v[160:161], v[160:161], s[40:41]
	v_pk_mul_f32 v[162:163], v[162:163], s[40:41]
	v_pk_mul_f32 v[164:165], v[164:165], s[40:41]
	v_pk_mul_f32 v[166:167], v[166:167], s[40:41]
	v_pk_mul_f32 v[168:169], v[168:169], s[40:41]
	v_pk_mul_f32 v[170:171], v[170:171], s[40:41]
	v_pk_mul_f32 v[172:173], v[172:173], s[40:41]
	v_pk_mul_f32 v[174:175], v[174:175], s[40:41]
	v_pk_mul_f32 v[176:177], v[176:177], s[40:41]
	v_pk_mul_f32 v[178:179], v[178:179], s[40:41]
	v_pk_mul_f32 v[180:181], v[180:181], s[40:41]
	v_pk_mul_f32 v[182:183], v[182:183], s[40:41]
	v_pk_mul_f32 v[186:187], v[186:187], s[40:41]
	v_pk_mul_f32 v[188:189], v[188:189], s[40:41]
	v_pk_mul_f32 v[190:191], v[190:191], s[40:41]
	v_pk_mul_f32 v[192:193], v[192:193], s[40:41]
	v_cvt_pk_fp8_f32 v128, v128, v132
	v_cvt_pk_fp8_f32 v129, v129, v133
	v_cvt_pk_fp8_f32 v130, v130, v134
	v_cvt_pk_fp8_f32 v131, v131, v135
	v_cvt_pk_fp8_f32 v128, v136, v140 op_sel:[0,0,1]
	v_cvt_pk_fp8_f32 v129, v137, v141 op_sel:[0,0,1]
	v_cvt_pk_fp8_f32 v130, v138, v142 op_sel:[0,0,1]
	v_cvt_pk_fp8_f32 v131, v139, v143 op_sel:[0,0,1]
	v_cvt_pk_fp8_f32 v144, v144, v148
	v_cvt_pk_fp8_f32 v145, v145, v149
	v_cvt_pk_fp8_f32 v146, v146, v150
	v_cvt_pk_fp8_f32 v147, v147, v151
	v_cvt_pk_fp8_f32 v144, v152, v156 op_sel:[0,0,1]
	v_cvt_pk_fp8_f32 v145, v153, v157 op_sel:[0,0,1]
	v_cvt_pk_fp8_f32 v146, v154, v158 op_sel:[0,0,1]
	v_cvt_pk_fp8_f32 v147, v155, v159 op_sel:[0,0,1]
	v_cvt_pk_fp8_f32 v160, v160, v164
	v_cvt_pk_fp8_f32 v161, v161, v165
	v_cvt_pk_fp8_f32 v162, v162, v166
	v_cvt_pk_fp8_f32 v163, v163, v167
	v_cvt_pk_fp8_f32 v160, v168, v172 op_sel:[0,0,1]
	v_cvt_pk_fp8_f32 v161, v169, v173 op_sel:[0,0,1]
	v_cvt_pk_fp8_f32 v162, v170, v174 op_sel:[0,0,1]
	v_cvt_pk_fp8_f32 v163, v171, v175 op_sel:[0,0,1]
	v_cvt_pk_fp8_f32 v176, v176, v180
	v_cvt_pk_fp8_f32 v177, v177, v181
	v_cvt_pk_fp8_f32 v178, v178, v182
	v_cvt_pk_fp8_f32 v179, v179, v183
	v_cvt_pk_fp8_f32 v176, v186, v190 op_sel:[0,0,1]
	v_cvt_pk_fp8_f32 v177, v187, v191 op_sel:[0,0,1]
	v_cvt_pk_fp8_f32 v178, v188, v192 op_sel:[0,0,1]
	v_cvt_pk_fp8_f32 v179, v189, v193 op_sel:[0,0,1]
	s_nop 0
	ds_write2_b32 v198, v128, v144 offset0:0 offset1:8
	ds_write2_b32 v198, v160, v176 offset0:16 offset1:24
	ds_write2_b32 v198, v129, v145 offset0:36 offset1:44
	ds_write2_b32 v198, v161, v177 offset0:52 offset1:60
	ds_write2_b32 v198, v130, v146 offset0:72 offset1:80
	ds_write2_b32 v198, v162, v178 offset0:88 offset1:96
	ds_write2_b32 v198, v131, v147 offset0:108 offset1:116
	ds_write2_b32 v198, v163, v179 offset0:124 offset1:132
	v_lshlrev_b32_e32 v136, s59, v200
	v_add_u32_e32 v136, v136, v201
	s_add_u32 s45, s59, 3
	s_lshl_b32 s4, 1, s45
	v_add_u32_e32 v152, s4, v136
	v_add_u32_e32 v168, s4, v152
	v_add_u32_e32 v186, s4, v168
	s_waitcnt lgkmcnt(0)
	ds_read_b128 v[132:135], v199 offset:0
	ds_read_b128 v[148:151], v199 offset:1152
	ds_read_b128 v[164:167], v199 offset:2304
	ds_read_b128 v[180:183], v199 offset:3456
	s_waitcnt lgkmcnt(3)
	global_store_dwordx4 v136, v[132:135], s[92:93] sc1
	s_waitcnt lgkmcnt(2)
	global_store_dwordx4 v152, v[148:151], s[92:93] sc1
	s_waitcnt lgkmcnt(1)
	global_store_dwordx4 v168, v[164:167], s[92:93] sc1
	s_waitcnt lgkmcnt(0)
	global_store_dwordx4 v186, v[180:183], s[92:93] sc1
	s_mov_b32 s18, 3

.Lcp_md_5:
	s_add_u32 s45, s43, 7
	s_lshl_b32 s53, s5, s45
	s_lshl_b32 s4, s1, 7
	s_add_u32 s53, s53, s4
	s_add_u32 s80, s6, s53
	s_addc_u32 s81, s7, 0
	s_add_u32 s45, s43, 5
	s_lshl_b32 s4, 1, s45
	s_add_u32 s82, s80, s4
	s_addc_u32 s83, s81, 0
	s_add_u32 s84, s82, s4
	s_addc_u32 s85, s83, 0
	s_add_u32 s86, s84, s4
	s_addc_u32 s87, s85, 0
	s_add_u32 s45, s59, 5
	s_lshl_b32 s4, s1, s45
	s_lshl_b32 s5, s5, 7
	s_add_u32 s4, s4, s5
	s_add_u32 s92, s8, s4
	s_addc_u32 s93, s9, 0
	s_add_u32 s45, s43, 2
	v_lshlrev_b32_e32 v194, s45, v200
	v_add_u32_e32 v194, v194, v201
	s_lshl_b32 s4, 1, s43
	v_add_u32_e32 v195, s4, v194
	v_add_u32_e32 v196, s4, v195
	v_add_u32_e32 v197, s4, v196
	global_load_dwordx4 v[128:131], v194, s[80:81]
	global_load_dwordx4 v[132:135], v195, s[80:81]
	global_load_dwordx4 v[136:139], v196, s[80:81]
	global_load_dwordx4 v[140:143], v197, s[80:81]
	global_load_dwordx4 v[144:147], v194, s[82:83]
	global_load_dwordx4 v[148:151], v195, s[82:83]
	global_load_dwordx4 v[152:155], v196, s[82:83]
	global_load_dwordx4 v[156:159], v197, s[82:83]
	global_load_dwordx4 v[160:163], v194, s[84:85]
	global_load_dwordx4 v[164:167], v195, s[84:85]
	global_load_dwordx4 v[168:171], v196, s[84:85]
	global_load_dwordx4 v[172:175], v197, s[84:85]
	global_load_dwordx4 v[176:179], v194, s[86:87]
	global_load_dwordx4 v[180:183], v195, s[86:87]
	global_load_dwordx4 v[186:189], v196, s[86:87]
	global_load_dwordx4 v[190:193], v197, s[86:87]
	s_waitcnt vmcnt(40)
	v_pk_mul_f32 v[0:1], v[0:1], s[40:41]
	v_pk_mul_f32 v[2:3], v[2:3], s[40:41]
	v_pk_mul_f32 v[4:5], v[4:5], s[40:41]
	v_pk_mul_f32 v[6:7], v[6:7], s[40:41]
	v_pk_mul_f32 v[8:9], v[8:9], s[40:41]
	v_pk_mul_f32 v[10:11], v[10:11], s[40:41]
	v_pk_mul_f32 v[12:13], v[12:13], s[40:41]
	v_pk_mul_f32 v[14:15], v[14:15], s[40:41]
	v_pk_mul_f32 v[16:17], v[16:17], s[40:41]
	v_pk_mul_f32 v[18:19], v[18:19], s[40:41]
	v_pk_mul_f32 v[20:21], v[20:21], s[40:41]
	v_pk_mul_f32 v[22:23], v[22:23], s[40:41]
	v_pk_mul_f32 v[24:25], v[24:25], s[40:41]
	v_pk_mul_f32 v[26:27], v[26:27], s[40:41]
	v_pk_mul_f32 v[28:29], v[28:29], s[40:41]
	v_pk_mul_f32 v[30:31], v[30:31], s[40:41]
	v_pk_mul_f32 v[32:33], v[32:33], s[40:41]
	v_pk_mul_f32 v[34:35], v[34:35], s[40:41]
	v_pk_mul_f32 v[36:37], v[36:37], s[40:41]
	v_pk_mul_f32 v[38:39], v[38:39], s[40:41]
	v_pk_mul_f32 v[40:41], v[40:41], s[40:41]
	v_pk_mul_f32 v[42:43], v[42:43], s[40:41]
	v_pk_mul_f32 v[44:45], v[44:45], s[40:41]
	v_pk_mul_f32 v[46:47], v[46:47], s[40:41]
	v_pk_mul_f32 v[48:49], v[48:49], s[40:41]
	v_pk_mul_f32 v[50:51], v[50:51], s[40:41]
	v_pk_mul_f32 v[52:53], v[52:53], s[40:41]
	v_pk_mul_f32 v[54:55], v[54:55], s[40:41]
	v_pk_mul_f32 v[56:57], v[56:57], s[40:41]
	v_pk_mul_f32 v[58:59], v[58:59], s[40:41]
	v_pk_mul_f32 v[60:61], v[60:61], s[40:41]
	v_pk_mul_f32 v[62:63], v[62:63], s[40:41]
	v_cvt_pk_fp8_f32 v0, v0, v4
	v_cvt_pk_fp8_f32 v1, v1, v5
	v_cvt_pk_fp8_f32 v2, v2, v6
	v_cvt_pk_fp8_f32 v3, v3, v7
	v_cvt_pk_fp8_f32 v0, v8, v12 op_sel:[0,0,1]
	v_cvt_pk_fp8_f32 v1, v9, v13 op_sel:[0,0,1]
	v_cvt_pk_fp8_f32 v2, v10, v14 op_sel:[0,0,1]
	v_cvt_pk_fp8_f32 v3, v11, v15 op_sel:[0,0,1]
	v_cvt_pk_fp8_f32 v16, v16, v20
	v_cvt_pk_fp8_f32 v17, v17, v21
	v_cvt_pk_fp8_f32 v18, v18, v22
	v_cvt_pk_fp8_f32 v19, v19, v23
	v_cvt_pk_fp8_f32 v16, v24, v28 op_sel:[0,0,1]
	v_cvt_pk_fp8_f32 v17, v25, v29 op_sel:[0,0,1]
	v_cvt_pk_fp8_f32 v18, v26, v30 op_sel:[0,0,1]
	v_cvt_pk_fp8_f32 v19, v27, v31 op_sel:[0,0,1]
	v_cvt_pk_fp8_f32 v32, v32, v36
	v_cvt_pk_fp8_f32 v33, v33, v37
	v_cvt_pk_fp8_f32 v34, v34, v38
	v_cvt_pk_fp8_f32 v35, v35, v39
	v_cvt_pk_fp8_f32 v32, v40, v44 op_sel:[0,0,1]
	v_cvt_pk_fp8_f32 v33, v41, v45 op_sel:[0,0,1]
	v_cvt_pk_fp8_f32 v34, v42, v46 op_sel:[0,0,1]
	v_cvt_pk_fp8_f32 v35, v43, v47 op_sel:[0,0,1]
	v_cvt_pk_fp8_f32 v48, v48, v52
	v_cvt_pk_fp8_f32 v49, v49, v53
	v_cvt_pk_fp8_f32 v50, v50, v54
	v_cvt_pk_fp8_f32 v51, v51, v55
	v_cvt_pk_fp8_f32 v48, v56, v60 op_sel:[0,0,1]
	v_cvt_pk_fp8_f32 v49, v57, v61 op_sel:[0,0,1]
	v_cvt_pk_fp8_f32 v50, v58, v62 op_sel:[0,0,1]
	v_cvt_pk_fp8_f32 v51, v59, v63 op_sel:[0,0,1]
	s_nop 0
	ds_write2_b32 v198, v0, v16 offset0:0 offset1:8
	ds_write2_b32 v198, v32, v48 offset0:16 offset1:24
	ds_write2_b32 v198, v1, v17 offset0:36 offset1:44
	ds_write2_b32 v198, v33, v49 offset0:52 offset1:60
	ds_write2_b32 v198, v2, v18 offset0:72 offset1:80
	ds_write2_b32 v198, v34, v50 offset0:88 offset1:96
	ds_write2_b32 v198, v3, v19 offset0:108 offset1:116
	ds_write2_b32 v198, v35, v51 offset0:124 offset1:132
	v_lshlrev_b32_e32 v8, s55, v200
	v_add_u32_e32 v8, v8, v201
	s_add_u32 s45, s55, 3
	s_lshl_b32 s4, 1, s45
	v_add_u32_e32 v24, s4, v8
	v_add_u32_e32 v40, s4, v24
	v_add_u32_e32 v56, s4, v40
	s_waitcnt lgkmcnt(0)
	ds_read_b128 v[4:7], v199 offset:0
	ds_read_b128 v[20:23], v199 offset:1152
	ds_read_b128 v[36:39], v199 offset:2304
	ds_read_b128 v[52:55], v199 offset:3456
	s_waitcnt lgkmcnt(3)
	global_store_dwordx4 v8, v[4:7], s[88:89] sc1
	s_waitcnt lgkmcnt(2)
	global_store_dwordx4 v24, v[20:23], s[88:89] sc1
	s_waitcnt lgkmcnt(1)
	global_store_dwordx4 v40, v[36:39], s[88:89] sc1
	s_waitcnt lgkmcnt(0)
	global_store_dwordx4 v56, v[52:55], s[88:89] sc1
	s_min_u32 s5, s3, 9215
	s_add_u32 s3, s3, 384
	s_cmp_lt_u32 s5, 0x400
	s_cbranch_scc1 .Lcp_m0_6
	s_cmp_lt_u32 s5, 0x1400
	s_cbranch_scc1 .Lcp_m1_6
	s_sub_u32 s5, s5, 0x1400
	s_and_b32 s1, s5, 63
	s_lshr_b32 s5, s5, 6
	s_mov_b32 s43, 13
	s_mov_b32 s55, 13
	s_mov_b64 s[6:7], s[94:95]
	s_add_u32 s8, s28, 0x4500000
	s_addc_u32 s9, s29, 0
	s_branch .Lcp_md_6

.Lcp_md_6:
	s_add_u32 s45, s43, 7
	s_lshl_b32 s53, s5, s45
	s_lshl_b32 s4, s1, 7
	s_add_u32 s53, s53, s4
	s_add_u32 s80, s6, s53
	s_addc_u32 s81, s7, 0
	s_add_u32 s45, s43, 5
	s_lshl_b32 s4, 1, s45
	s_add_u32 s82, s80, s4
	s_addc_u32 s83, s81, 0
	s_add_u32 s84, s82, s4
	s_addc_u32 s85, s83, 0
	s_add_u32 s86, s84, s4
	s_addc_u32 s87, s85, 0
	s_add_u32 s45, s55, 5
	s_lshl_b32 s4, s1, s45
	s_lshl_b32 s5, s5, 7
	s_add_u32 s4, s4, s5
	s_add_u32 s88, s8, s4
	s_addc_u32 s89, s9, 0
	s_add_u32 s45, s43, 2
	v_lshlrev_b32_e32 v194, s45, v200
	v_add_u32_e32 v194, v194, v201
	s_lshl_b32 s4, 1, s43
	v_add_u32_e32 v195, s4, v194
	v_add_u32_e32 v196, s4, v195
	v_add_u32_e32 v197, s4, v196
	global_load_dwordx4 v[0:3], v194, s[80:81]
	global_load_dwordx4 v[4:7], v195, s[80:81]
	global_load_dwordx4 v[8:11], v196, s[80:81]
	global_load_dwordx4 v[12:15], v197, s[80:81]
	global_load_dwordx4 v[16:19], v194, s[82:83]
	global_load_dwordx4 v[20:23], v195, s[82:83]
	global_load_dwordx4 v[24:27], v196, s[82:83]
	global_load_dwordx4 v[28:31], v197, s[82:83]
	global_load_dwordx4 v[32:35], v194, s[84:85]
	global_load_dwordx4 v[36:39], v195, s[84:85]
	global_load_dwordx4 v[40:43], v196, s[84:85]
	global_load_dwordx4 v[44:47], v197, s[84:85]
	global_load_dwordx4 v[48:51], v194, s[86:87]
	global_load_dwordx4 v[52:55], v195, s[86:87]
	global_load_dwordx4 v[56:59], v196, s[86:87]
	global_load_dwordx4 v[60:63], v197, s[86:87]
	s_waitcnt vmcnt(40)
	v_pk_mul_f32 v[64:65], v[64:65], s[40:41]
	v_pk_mul_f32 v[66:67], v[66:67], s[40:41]
	v_pk_mul_f32 v[68:69], v[68:69], s[40:41]
	v_pk_mul_f32 v[70:71], v[70:71], s[40:41]
	v_pk_mul_f32 v[72:73], v[72:73], s[40:41]
	v_pk_mul_f32 v[74:75], v[74:75], s[40:41]
	v_pk_mul_f32 v[76:77], v[76:77], s[40:41]
	v_pk_mul_f32 v[78:79], v[78:79], s[40:41]
	v_pk_mul_f32 v[80:81], v[80:81], s[40:41]
	v_pk_mul_f32 v[82:83], v[82:83], s[40:41]
	v_pk_mul_f32 v[84:85], v[84:85], s[40:41]
	v_pk_mul_f32 v[86:87], v[86:87], s[40:41]
	v_pk_mul_f32 v[88:89], v[88:89], s[40:41]
	v_pk_mul_f32 v[90:91], v[90:91], s[40:41]
	v_pk_mul_f32 v[92:93], v[92:93], s[40:41]
	v_pk_mul_f32 v[94:95], v[94:95], s[40:41]
	v_pk_mul_f32 v[96:97], v[96:97], s[40:41]
	v_pk_mul_f32 v[98:99], v[98:99], s[40:41]
	v_pk_mul_f32 v[100:101], v[100:101], s[40:41]
	v_pk_mul_f32 v[102:103], v[102:103], s[40:41]
	v_pk_mul_f32 v[104:105], v[104:105], s[40:41]
	v_pk_mul_f32 v[106:107], v[106:107], s[40:41]
	v_pk_mul_f32 v[108:109], v[108:109], s[40:41]
	v_pk_mul_f32 v[110:111], v[110:111], s[40:41]
	v_pk_mul_f32 v[112:113], v[112:113], s[40:41]
	v_pk_mul_f32 v[114:115], v[114:115], s[40:41]
	v_pk_mul_f32 v[116:117], v[116:117], s[40:41]
	v_pk_mul_f32 v[118:119], v[118:119], s[40:41]
	v_pk_mul_f32 v[120:121], v[120:121], s[40:41]
	v_pk_mul_f32 v[122:123], v[122:123], s[40:41]
	v_pk_mul_f32 v[124:125], v[124:125], s[40:41]
	v_pk_mul_f32 v[126:127], v[126:127], s[40:41]
	v_cvt_pk_fp8_f32 v64, v64, v68
	v_cvt_pk_fp8_f32 v65, v65, v69
	v_cvt_pk_fp8_f32 v66, v66, v70
	v_cvt_pk_fp8_f32 v67, v67, v71
	v_cvt_pk_fp8_f32 v64, v72, v76 op_sel:[0,0,1]
	v_cvt_pk_fp8_f32 v65, v73, v77 op_sel:[0,0,1]
	v_cvt_pk_fp8_f32 v66, v74, v78 op_sel:[0,0,1]
	v_cvt_pk_fp8_f32 v67, v75, v79 op_sel:[0,0,1]
	v_cvt_pk_fp8_f32 v80, v80, v84
	v_cvt_pk_fp8_f32 v81, v81, v85
	v_cvt_pk_fp8_f32 v82, v82, v86
	v_cvt_pk_fp8_f32 v83, v83, v87
	v_cvt_pk_fp8_f32 v80, v88, v92 op_sel:[0,0,1]
	v_cvt_pk_fp8_f32 v81, v89, v93 op_sel:[0,0,1]
	v_cvt_pk_fp8_f32 v82, v90, v94 op_sel:[0,0,1]
	v_cvt_pk_fp8_f32 v83, v91, v95 op_sel:[0,0,1]
	v_cvt_pk_fp8_f32 v96, v96, v100
	v_cvt_pk_fp8_f32 v97, v97, v101
	v_cvt_pk_fp8_f32 v98, v98, v102
	v_cvt_pk_fp8_f32 v99, v99, v103
	v_cvt_pk_fp8_f32 v96, v104, v108 op_sel:[0,0,1]
	v_cvt_pk_fp8_f32 v97, v105, v109 op_sel:[0,0,1]
	v_cvt_pk_fp8_f32 v98, v106, v110 op_sel:[0,0,1]
	v_cvt_pk_fp8_f32 v99, v107, v111 op_sel:[0,0,1]
	v_cvt_pk_fp8_f32 v112, v112, v116
	v_cvt_pk_fp8_f32 v113, v113, v117
	v_cvt_pk_fp8_f32 v114, v114, v118
	v_cvt_pk_fp8_f32 v115, v115, v119
	v_cvt_pk_fp8_f32 v112, v120, v124 op_sel:[0,0,1]
	v_cvt_pk_fp8_f32 v113, v121, v125 op_sel:[0,0,1]
	v_cvt_pk_fp8_f32 v114, v122, v126 op_sel:[0,0,1]
	v_cvt_pk_fp8_f32 v115, v123, v127 op_sel:[0,0,1]
	s_nop 0
	ds_write2_b32 v198, v64, v80 offset0:0 offset1:8
	ds_write2_b32 v198, v96, v112 offset0:16 offset1:24
	ds_write2_b32 v198, v65, v81 offset0:36 offset1:44
	ds_write2_b32 v198, v97, v113 offset0:52 offset1:60
	ds_write2_b32 v198, v66, v82 offset0:72 offset1:80
	ds_write2_b32 v198, v98, v114 offset0:88 offset1:96
	ds_write2_b32 v198, v67, v83 offset0:108 offset1:116
	ds_write2_b32 v198, v99, v115 offset0:124 offset1:132
	v_lshlrev_b32_e32 v72, s58, v200
	v_add_u32_e32 v72, v72, v201
	s_add_u32 s45, s58, 3
	s_lshl_b32 s4, 1, s45
	v_add_u32_e32 v88, s4, v72
	v_add_u32_e32 v104, s4, v88
	v_add_u32_e32 v120, s4, v104
	s_waitcnt lgkmcnt(0)
	ds_read_b128 v[68:71], v199 offset:0
	ds_read_b128 v[84:87], v199 offset:1152
	ds_read_b128 v[100:103], v199 offset:2304
	ds_read_b128 v[116:119], v199 offset:3456
	s_waitcnt lgkmcnt(3)
	global_store_dwordx4 v72, v[68:71], s[90:91] sc1
	s_waitcnt lgkmcnt(2)
	global_store_dwordx4 v88, v[84:87], s[90:91] sc1
	s_waitcnt lgkmcnt(1)
	global_store_dwordx4 v104, v[100:103], s[90:91] sc1
	s_waitcnt lgkmcnt(0)
	global_store_dwordx4 v120, v[116:119], s[90:91] sc1
	s_min_u32 s5, s3, 9215
	s_add_u32 s3, s3, 384
	s_cmp_lt_u32 s5, 0x400
	s_cbranch_scc1 .Lcp_m0_7
	s_cmp_lt_u32 s5, 0x1400
	s_cbranch_scc1 .Lcp_m1_7
	s_sub_u32 s5, s5, 0x1400
	s_and_b32 s1, s5, 63
	s_lshr_b32 s5, s5, 6
	s_mov_b32 s43, 13
	s_mov_b32 s58, 13
	s_mov_b64 s[6:7], s[94:95]
	s_add_u32 s8, s28, 0x4500000
	s_addc_u32 s9, s29, 0
	s_branch .Lcp_md_7

.Lcp_md_7:
	s_add_u32 s45, s43, 7
	s_lshl_b32 s53, s5, s45
	s_lshl_b32 s4, s1, 7
	s_add_u32 s53, s53, s4
	s_add_u32 s80, s6, s53
	s_addc_u32 s81, s7, 0
	s_add_u32 s45, s43, 5
	s_lshl_b32 s4, 1, s45
	s_add_u32 s82, s80, s4
	s_addc_u32 s83, s81, 0
	s_add_u32 s84, s82, s4
	s_addc_u32 s85, s83, 0
	s_add_u32 s86, s84, s4
	s_addc_u32 s87, s85, 0
	s_add_u32 s45, s58, 5
	s_lshl_b32 s4, s1, s45
	s_lshl_b32 s5, s5, 7
	s_add_u32 s4, s4, s5
	s_add_u32 s90, s8, s4
	s_addc_u32 s91, s9, 0
	s_add_u32 s45, s43, 2
	v_lshlrev_b32_e32 v194, s45, v200
	v_add_u32_e32 v194, v194, v201
	s_lshl_b32 s4, 1, s43
	v_add_u32_e32 v195, s4, v194
	v_add_u32_e32 v196, s4, v195
	v_add_u32_e32 v197, s4, v196
	global_load_dwordx4 v[64:67], v194, s[80:81]
	global_load_dwordx4 v[68:71], v195, s[80:81]
	global_load_dwordx4 v[72:75], v196, s[80:81]
	global_load_dwordx4 v[76:79], v197, s[80:81]
	global_load_dwordx4 v[80:83], v194, s[82:83]
	global_load_dwordx4 v[84:87], v195, s[82:83]
	global_load_dwordx4 v[88:91], v196, s[82:83]
	global_load_dwordx4 v[92:95], v197, s[82:83]
	global_load_dwordx4 v[96:99], v194, s[84:85]
	global_load_dwordx4 v[100:103], v195, s[84:85]
	global_load_dwordx4 v[104:107], v196, s[84:85]
	global_load_dwordx4 v[108:111], v197, s[84:85]
	global_load_dwordx4 v[112:115], v194, s[86:87]
	global_load_dwordx4 v[116:119], v195, s[86:87]
	global_load_dwordx4 v[120:123], v196, s[86:87]
	global_load_dwordx4 v[124:127], v197, s[86:87]
	s_waitcnt vmcnt(40)
	v_pk_mul_f32 v[128:129], v[128:129], s[40:41]
	v_pk_mul_f32 v[130:131], v[130:131], s[40:41]
	v_pk_mul_f32 v[132:133], v[132:133], s[40:41]
	v_pk_mul_f32 v[134:135], v[134:135], s[40:41]
	v_pk_mul_f32 v[136:137], v[136:137], s[40:41]
	v_pk_mul_f32 v[138:139], v[138:139], s[40:41]
	v_pk_mul_f32 v[140:141], v[140:141], s[40:41]
	v_pk_mul_f32 v[142:143], v[142:143], s[40:41]
	v_pk_mul_f32 v[144:145], v[144:145], s[40:41]
	v_pk_mul_f32 v[146:147], v[146:147], s[40:41]
	v_pk_mul_f32 v[148:149], v[148:149], s[40:41]
	v_pk_mul_f32 v[150:151], v[150:151], s[40:41]
	v_pk_mul_f32 v[152:153], v[152:153], s[40:41]
	v_pk_mul_f32 v[154:155], v[154:155], s[40:41]
	v_pk_mul_f32 v[156:157], v[156:157], s[40:41]
	v_pk_mul_f32 v[158:159], v[158:159], s[40:41]
	v_pk_mul_f32 v[160:161], v[160:161], s[40:41]
	v_pk_mul_f32 v[162:163], v[162:163], s[40:41]
	v_pk_mul_f32 v[164:165], v[164:165], s[40:41]
	v_pk_mul_f32 v[166:167], v[166:167], s[40:41]
	v_pk_mul_f32 v[168:169], v[168:169], s[40:41]
	v_pk_mul_f32 v[170:171], v[170:171], s[40:41]
	v_pk_mul_f32 v[172:173], v[172:173], s[40:41]
	v_pk_mul_f32 v[174:175], v[174:175], s[40:41]
	v_pk_mul_f32 v[176:177], v[176:177], s[40:41]
	v_pk_mul_f32 v[178:179], v[178:179], s[40:41]
	v_pk_mul_f32 v[180:181], v[180:181], s[40:41]
	v_pk_mul_f32 v[182:183], v[182:183], s[40:41]
	v_pk_mul_f32 v[186:187], v[186:187], s[40:41]
	v_pk_mul_f32 v[188:189], v[188:189], s[40:41]
	v_pk_mul_f32 v[190:191], v[190:191], s[40:41]
	v_pk_mul_f32 v[192:193], v[192:193], s[40:41]
	v_cvt_pk_fp8_f32 v128, v128, v132
	v_cvt_pk_fp8_f32 v129, v129, v133
	v_cvt_pk_fp8_f32 v130, v130, v134
	v_cvt_pk_fp8_f32 v131, v131, v135
	v_cvt_pk_fp8_f32 v128, v136, v140 op_sel:[0,0,1]
	v_cvt_pk_fp8_f32 v129, v137, v141 op_sel:[0,0,1]
	v_cvt_pk_fp8_f32 v130, v138, v142 op_sel:[0,0,1]
	v_cvt_pk_fp8_f32 v131, v139, v143 op_sel:[0,0,1]
	v_cvt_pk_fp8_f32 v144, v144, v148
	v_cvt_pk_fp8_f32 v145, v145, v149
	v_cvt_pk_fp8_f32 v146, v146, v150
	v_cvt_pk_fp8_f32 v147, v147, v151
	v_cvt_pk_fp8_f32 v144, v152, v156 op_sel:[0,0,1]
	v_cvt_pk_fp8_f32 v145, v153, v157 op_sel:[0,0,1]
	v_cvt_pk_fp8_f32 v146, v154, v158 op_sel:[0,0,1]
	v_cvt_pk_fp8_f32 v147, v155, v159 op_sel:[0,0,1]
	v_cvt_pk_fp8_f32 v160, v160, v164
	v_cvt_pk_fp8_f32 v161, v161, v165
	v_cvt_pk_fp8_f32 v162, v162, v166
	v_cvt_pk_fp8_f32 v163, v163, v167
	v_cvt_pk_fp8_f32 v160, v168, v172 op_sel:[0,0,1]
	v_cvt_pk_fp8_f32 v161, v169, v173 op_sel:[0,0,1]
	v_cvt_pk_fp8_f32 v162, v170, v174 op_sel:[0,0,1]
	v_cvt_pk_fp8_f32 v163, v171, v175 op_sel:[0,0,1]
	v_cvt_pk_fp8_f32 v176, v176, v180
	v_cvt_pk_fp8_f32 v177, v177, v181
	v_cvt_pk_fp8_f32 v178, v178, v182
	v_cvt_pk_fp8_f32 v179, v179, v183
	v_cvt_pk_fp8_f32 v176, v186, v190 op_sel:[0,0,1]
	v_cvt_pk_fp8_f32 v177, v187, v191 op_sel:[0,0,1]
	v_cvt_pk_fp8_f32 v178, v188, v192 op_sel:[0,0,1]
	v_cvt_pk_fp8_f32 v179, v189, v193 op_sel:[0,0,1]
	s_nop 0
	ds_write2_b32 v198, v128, v144 offset0:0 offset1:8
	ds_write2_b32 v198, v160, v176 offset0:16 offset1:24
	ds_write2_b32 v198, v129, v145 offset0:36 offset1:44
	ds_write2_b32 v198, v161, v177 offset0:52 offset1:60
	ds_write2_b32 v198, v130, v146 offset0:72 offset1:80
	ds_write2_b32 v198, v162, v178 offset0:88 offset1:96
	ds_write2_b32 v198, v131, v147 offset0:108 offset1:116
	ds_write2_b32 v198, v163, v179 offset0:124 offset1:132
	v_lshlrev_b32_e32 v136, s59, v200
	v_add_u32_e32 v136, v136, v201
	s_add_u32 s45, s59, 3
	s_lshl_b32 s4, 1, s45
	v_add_u32_e32 v152, s4, v136
	v_add_u32_e32 v168, s4, v152
	v_add_u32_e32 v186, s4, v168
	s_waitcnt lgkmcnt(0)
	ds_read_b128 v[132:135], v199 offset:0
	ds_read_b128 v[148:151], v199 offset:1152
	ds_read_b128 v[164:167], v199 offset:2304
	ds_read_b128 v[180:183], v199 offset:3456
	s_waitcnt lgkmcnt(3)
	global_store_dwordx4 v136, v[132:135], s[92:93] sc1
	s_waitcnt lgkmcnt(2)
	global_store_dwordx4 v152, v[148:151], s[92:93] sc1
	s_waitcnt lgkmcnt(1)
	global_store_dwordx4 v168, v[164:167], s[92:93] sc1
	s_waitcnt lgkmcnt(0)
	global_store_dwordx4 v186, v[180:183], s[92:93] sc1
	s_add_u32 s18, s18, 3
	s_cmp_lt_u32 s18, 24
	s_cbranch_scc1 .Lcp_loop
	s_waitcnt vmcnt(0)
	v_mov_b32_e32 v108, v184
	v_and_b32_e32 v146, 63, v108
	s_branch .Lscan_setup
